# P7a AbT/P1T products share the T fragments (8 LDS reads instead of 12, all up front)
# baseline (speedup 1.0000x reference)
; __device__ __forceinline__ void st_bf4(LAS bf16_t* p, f32x4 v) { u32x2 w; w.x = pk2(v.x, v.y); w.y = pk2(v.z, v.w); *(LAS u32x2*)p = w; }
; __device__ __forceinline__ void chunk_pre(const Params& p, LAS unsigned char* lds, int item, int next_item, int tid, int wave, int lane, h16 (&raw)[48]) {
;     ...
;     {
;         f32x4 acc[2];
;         acc[0] = (f32x4){0.f, 0.f, 0.f, 0.f}; acc[1] = acc[0]; mm64(Tb, AtT, acc, wave, fr, fq);
; #pragma unroll
;         for (int nt = 0; nt < 2; ++nt) st_bf4(AbT + ar * MS + 32 * (wave & 1) + 16 * nt + 4 * fq, acc[nt]);
;         acc[0] = (f32x4){0.f, 0.f, 0.f, 0.f}; acc[1] = acc[0]; mm64(Tb, RH2T, acc, wave, fr, fq);
; #pragma unroll
;         for (int nt = 0; nt < 2; ++nt) st_bf4(P1T + ar * MS + 32 * (wave & 1) + 16 * nt + 4 * fq, acc[nt]);
;     }
.LBB0_922:
	s_or_b64 exec, exec, s[12:13]
	s_waitcnt lgkmcnt(0)
	s_barrier
	ds_read_b128 v[236:239], v132
	ds_read_b128 v[220:223], v161
	ds_read_b128 v[224:227], v161 offset:2304
	ds_read_b128 v[240:243], v132 offset:64
	ds_read_b128 v[228:231], v161 offset:64
	ds_read_b128 v[232:235], v161 offset:2368
	ds_read_b128 v[184:187], v133
	ds_read_b128 v[188:191], v133 offset:64
	s_ashr_i32 s12, s45, 7
	v_add_u32_e32 v20, 0x6800, v95
	s_ashr_i32 s13, s12, 31
	s_lshl_b32 s8, s45, 6
	s_lshl_b64 s[12:13], s[12:13], 13
	s_and_b32 s8, s8, 0x1fc0
	s_or_b32 s8, s12, s8
	s_mul_i32 s12, s13, 0x300
	s_mul_hi_u32 s13, s8, 0x300
	s_add_i32 s13, s13, s12
	s_mulk_i32 s8, 0x300
	s_add_u32 s80, s6, s8
	s_addc_u32 s81, s7, s13
	v_lshl_add_u64 v[180:181], s[80:81], 0, v[26:27]
	v_readlane_b32 s12, v244, 51
	v_readlane_b32 s13, v244, 52
	s_and_b64 vcc, exec, s[10:11]
	s_waitcnt lgkmcnt(2)
	v_mfma_f32_16x16x32_bf16 v[8:11], v[220:223], v[236:239], 0
	v_mfma_f32_16x16x32_bf16 v[4:7], v[224:227], v[236:239], 0
	v_mfma_f32_16x16x32_bf16 v[8:11], v[228:231], v[240:243], v[8:11]
	v_mfma_f32_16x16x32_bf16 v[4:7], v[232:235], v[240:243], v[4:7]
	s_waitcnt lgkmcnt(0)
	v_mfma_f32_16x16x32_bf16 v[12:15], v[220:223], v[184:187], 0
	v_mfma_f32_16x16x32_bf16 v[16:19], v[224:227], v[184:187], 0
	v_mfma_f32_16x16x32_bf16 v[12:15], v[228:231], v[188:191], v[12:15]
	v_mfma_f32_16x16x32_bf16 v[16:19], v[232:235], v[188:191], v[16:19]
	s_mov_b32 s45, s50
	s_nop 3
	v_cvt_pk_bf16_f32 v8, v8, v9
	v_cvt_pk_bf16_f32 v9, v10, v11
	v_cvt_pk_bf16_f32 v4, v4, v5
	v_cvt_pk_bf16_f32 v5, v6, v7
	v_add_u32_e32 v6, 0x2000, v159
	ds_write2_b64 v6, v[8:9], v[4:5] offset0:128 offset1:132
	v_cvt_pk_bf16_f32 v8, v12, v13
	v_cvt_pk_bf16_f32 v9, v14, v15
	v_cvt_pk_bf16_f32 v4, v16, v17
	v_cvt_pk_bf16_f32 v5, v18, v19
	v_add_u32_e32 v6, 0x4800, v159
	ds_write2_b64 v6, v[8:9], v[4:5] offset1:4
	s_waitcnt lgkmcnt(0)
	s_barrier
; #define LAS __attribute__((address_space(3)))
; __device__ __forceinline__ unsigned pk2(float lo, float hi) { const f32x2c v = {lo, hi}; const bf16x2c b = __builtin_convertvector(v, bf16x2c); return __builtin_bit_cast(unsigned, b); }
; __device__ __forceinline__ float bflo(unsigned w) { return __uint_as_float(w << 16); }
; __device__ __forceinline__ void chunk_pre(const Params& p, LAS unsigned char* lds, int item, int next_item, int tid, int wave, int lane, h16 (&raw)[48]) {
;     ...
;     {
;         f32x4 acc[2];
;         acc[0] = (f32x4){0.f, 0.f, 0.f, 0.f}; acc[1] = acc[0];
;         mm64(AbT, Mrb, acc, wave, fr, fq);
; #pragma unroll
;         for (int nt = 0; nt < 2; ++nt) { const int b0 = 32 * (wave & 1) + 16 * nt + 4 * fq; const u32x2 rw = *(const LAS u32x2*)(Rt + ar * MS + b0);
;             const f32x4 v = acc[nt] + (f32x4){bflo(rw.x), bfhi(rw.x), bflo(rw.y), bfhi(rw.y)};
;             u32x2 w; w.x = pk2(v.x, v.y); w.y = pk2(v.z, v.w); *(u32x2*)(base + (size_t)(ar * 6 + 2) * 64 + b0) = w; }
;         acc[0] = (f32x4){0.f, 0.f, 0.f, 0.f}; acc[1] = acc[0];
;         mm64(P1T, Mrb, acc, wave, fr, fq); mm64(VT, Mrk, acc, wave, fr, fq);
; #pragma unroll
;         for (int nt = 0; nt < 2; ++nt) { const int b0 = 32 * (wave & 1) + 16 * nt + 4 * fq; *(f32x4*)((float*)(base + (size_t)(ar * 6 + 3) * 64) + b0) = acc[nt]; }
;         acc[0] = (f32x4){0.f, 0.f, 0.f, 0.f}; acc[1] = acc[0];
;         mm64(AbT, BhT, acc, wave, fr, fq);
;         { float WL = 1.f;
; #pragma unroll
;           for (int q = 0; q < 8; ++q) WL *= GT[q * 64 + ar];
; #pragma unroll
;           for (int nt = 0; nt < 2; ++nt) { const int b0 = 32 * (wave & 1) + 16 * nt + 4 * fq; f32x4 v = acc[nt];
; #pragma unroll
;               for (int jj = 0; jj < 4; ++jj) if (b0 + jj == ar) v[jj] += WL;
;               u32x2 w; w.x = pk2(v.x, v.y); w.y = pk2(v.z, v.w); *(u32x2*)(base + (size_t)(ar * 6 + 0) * 64 + b0) = w; } }
;         acc[0] = (f32x4){0.f, 0.f, 0.f, 0.f}; acc[1] = acc[0];
;         mm64(BhT, P1T, acc, wave, fr, fq); mm64(KhT, VT, acc, wave, fr, fq);
; #pragma unroll
;         for (int nt = 0; nt < 2; ++nt) { const int b0 = 32 * (wave & 1) + 16 * nt + 4 * fq; const f32x4 v = acc[nt];
;             u32x2 w; w.x = pk2(v.x, v.y); w.y = pk2(v.z, v.w); *(u32x2*)(base + (size_t)(ar * 6 + 1) * 64 + b0) = w; }
;     }
	ds_read_b128 v[36:39], v134
	ds_read_b128 v[8:11], v161 offset:9216
	ds_read_b128 v[16:19], v161 offset:11520
	ds_read_b128 v[168:171], v134 offset:64
	ds_read_b128 v[4:7], v161 offset:9280
	ds_read2_b64 v[176:179], v20 offset0:128 offset1:132
	ds_read_b128 v[220:223], v161 offset:11584
	ds_read_b128 v[224:227], v161 offset:18432
	ds_read_b128 v[228:231], v161 offset:20736
	ds_read_b128 v[232:235], v161 offset:18496
	ds_read_b128 v[236:239], v161 offset:20800
	ds_read_b128 v[240:243], v135
	s_waitcnt lgkmcnt(10)
	v_mfma_f32_16x16x32_bf16 v[12:15], v[8:11], v[36:39], 0
	s_nop 0
	s_waitcnt lgkmcnt(6)
	v_lshlrev_b32_e32 v34, 16, v176
	v_mfma_f32_16x16x32_bf16 v[172:175], v[4:7], v[168:171], v[12:15]
	v_and_b32_e32 v35, 0xffff0000, v176
	v_lshlrev_b32_e32 v176, 16, v177
	v_and_b32_e32 v177, 0xffff0000, v177
	s_nop 0
	s_nop 0
	v_mfma_f32_16x16x32_bf16 v[164:167], v[16:19], v[36:39], 0
	s_nop 1
	v_add_f32_e64 v34, v172, v34
	v_add_f32_e64 v35, v173, v35
	v_pk_add_f32 v[174:175], v[174:175], v[176:177]
	v_cvt_pk_bf16_f32 v172, v34, v35
	s_waitcnt lgkmcnt(5)
	v_mfma_f32_16x16x32_bf16 v[164:167], v[220:223], v[168:171], v[164:167]
	v_lshlrev_b64 v[34:35], 1, v[24:25]
	v_cvt_pk_bf16_f32 v173, v174, v175
	v_lshl_add_u64 v[174:175], v[180:181], 0, v[34:35]
	global_store_dwordx2 v[174:175], v[172:173], off
	v_lshlrev_b32_e32 v172, 16, v178
	v_and_b32_e32 v173, 0xffff0000, v178
	v_lshlrev_b32_e32 v176, 16, v179
	v_and_b32_e32 v177, 0xffff0000, v179
	v_pk_add_f32 v[166:167], v[166:167], v[176:177]
	v_pk_add_f32 v[164:165], v[164:165], v[172:173]
	s_nop 0
	v_cvt_pk_bf16_f32 v164, v164, v165
	v_cvt_pk_bf16_f32 v165, v166, v167
	global_store_dwordx2 v[174:175], v[164:165], off offset:32
	s_nop 0
	s_nop 0
	s_waitcnt lgkmcnt(4)
	v_mfma_f32_16x16x32_bf16 v[164:167], v[224:227], v[36:39], 0
	s_waitcnt lgkmcnt(3)
	v_mfma_f32_16x16x32_bf16 v[36:39], v[228:231], v[36:39], 0
	s_nop 0
	s_waitcnt lgkmcnt(2)
	v_mfma_f32_16x16x32_bf16 v[164:167], v[232:235], v[168:171], v[164:167]
	s_nop 0
	s_waitcnt lgkmcnt(1)
	v_mfma_f32_16x16x32_bf16 v[36:39], v[236:239], v[168:171], v[36:39]
	ds_read_b128 v[172:175], v161 offset:55296
	ds_read_b128 v[224:227], v161 offset:57600
	s_nop 0
	s_nop 0
	s_waitcnt lgkmcnt(1)
	v_mfma_f32_16x16x32_bf16 v[164:167], v[172:175], v[240:243], v[164:167]
	s_nop 0
	s_waitcnt lgkmcnt(0)
	v_mfma_f32_16x16x32_bf16 v[36:39], v[224:227], v[240:243], v[36:39]
	ds_read_b128 v[168:171], v135 offset:64
	ds_read_b128 v[172:175], v161 offset:55360
	s_waitcnt lgkmcnt(0)
	v_mfma_f32_16x16x32_bf16 v[164:167], v[172:175], v[168:171], v[164:167]
	ds_read_b128 v[172:175], v161 offset:57664
	ds_read_b128 v[224:227], v91 offset:36864
	s_waitcnt lgkmcnt(1)
	v_mfma_f32_16x16x32_bf16 v[36:39], v[172:175], v[168:171], v[36:39]
	v_lshl_add_u64 v[168:169], s[80:81], 0, v[28:29]
	v_lshl_add_u64 v[168:169], v[24:25], 2, v[168:169]
	s_nop 2
	global_store_dwordx4 v[168:169], v[164:167], off
	s_nop 1
	global_store_dwordx4 v[168:169], v[36:39], off offset:64
	s_nop 0
	s_waitcnt lgkmcnt(0)
	v_mfma_f32_16x16x32_bf16 v[8:11], v[8:11], v[224:227], 0
	v_mfma_f32_16x16x32_bf16 v[16:19], v[16:19], v[224:227], 0
	ds_read_b128 v[36:39], v91 offset:36928
	ds_read2st64_b32 v[224:225], v136 offset1:1
	ds_read2st64_b32 v[226:227], v136 offset0:2 offset1:3
	ds_read2st64_b32 v[228:229], v136 offset0:4 offset1:5
	ds_read2st64_b32 v[230:231], v136 offset0:6 offset1:7
	ds_read_b128 v[232:235], v91 offset:18432
	ds_read_b128 v[236:239], v161 offset:36864
	ds_read_b128 v[240:243], v161 offset:39168
	s_waitcnt lgkmcnt(7)
	v_mfma_f32_16x16x32_bf16 v[4:7], v[4:7], v[36:39], v[8:11]
	v_mfma_f32_16x16x32_bf16 v[8:11], v[220:223], v[36:39], v[16:19]
	s_nop 0
	s_waitcnt lgkmcnt(6)
	v_mul_f32_e32 v14, v224, v225
	s_nop 0
	s_waitcnt lgkmcnt(5)
	v_mul_f32_e32 v12, v14, v226
	v_mul_f32_e32 v14, v12, v227
	s_nop 0
	s_waitcnt lgkmcnt(4)
	v_mul_f32_e32 v12, v14, v228
	v_mul_f32_e32 v14, v12, v229
	s_nop 0
	s_waitcnt lgkmcnt(3)
	v_mul_f32_e32 v12, v14, v230
	v_fma_f32 v16, v12, v231, v4
	v_cndmask_b32_e64 v4, v4, v16, s[12:13]
	v_readlane_b32 s12, v244, 53
	v_fma_f32 v16, v12, v231, v5
	v_readlane_b32 s13, v244, 54
	v_lshl_add_u64 v[14:15], s[80:81], 0, v[30:31]
	s_nop 0
	v_cndmask_b32_e64 v5, v5, v16, s[12:13]
	v_readlane_b32 s12, v244, 55
	v_fma_f32 v16, v12, v231, v6
	v_readlane_b32 s13, v244, 56
	v_cvt_pk_bf16_f32 v4, v4, v5
	s_nop 0
	v_cndmask_b32_e64 v6, v6, v16, s[12:13]
	v_fma_f32 v16, v12, v231, v7
	v_cndmask_b32_e64 v7, v7, v16, s[56:57]
	v_cvt_pk_bf16_f32 v5, v6, v7
	v_lshl_add_u64 v[6:7], v[14:15], 0, v[34:35]
	global_store_dwordx2 v[6:7], v[4:5], off
	v_fma_f32 v4, v12, v231, v8
	v_fma_f32 v5, v12, v231, v9
	v_cndmask_b32_e64 v4, v8, v4, s[88:89]
	v_cndmask_b32_e64 v5, v9, v5, s[4:5]
	v_fma_f32 v8, v12, v231, v10
	v_fma_f32 v9, v12, v231, v11
	v_cndmask_b32_e64 v8, v10, v8, s[0:1]
	v_cndmask_b32_e64 v9, v11, v9, s[68:69]
	v_cvt_pk_bf16_f32 v4, v4, v5
	v_cvt_pk_bf16_f32 v5, v8, v9
	global_store_dwordx2 v[6:7], v[4:5], off offset:32
	s_nop 0
	s_nop 0
	s_nop 0
	s_waitcnt lgkmcnt(1)
	v_mfma_f32_16x16x32_bf16 v[8:11], v[236:239], v[232:235], 0
	s_waitcnt lgkmcnt(0)
	v_mfma_f32_16x16x32_bf16 v[4:7], v[240:243], v[232:235], 0
	ds_read_b128 v[12:15], v91 offset:18496
	ds_read_b128 v[16:19], v161 offset:36928
	ds_read_b128 v[220:223], v161 offset:39232
	ds_read_b128 v[224:227], v91 offset:55296
	ds_read_b128 v[228:231], v161 offset:46080
	ds_read_b128 v[232:235], v161 offset:48384
	s_waitcnt lgkmcnt(4)
	v_mfma_f32_16x16x32_bf16 v[8:11], v[16:19], v[12:15], v[8:11]
	s_nop 0
	s_waitcnt lgkmcnt(3)
	v_mfma_f32_16x16x32_bf16 v[4:7], v[220:223], v[12:15], v[4:7]
	s_nop 0
	s_nop 0
	s_waitcnt lgkmcnt(1)
	v_mfma_f32_16x16x32_bf16 v[8:11], v[228:231], v[224:227], v[8:11]
	s_nop 0
	s_waitcnt lgkmcnt(0)
	v_mfma_f32_16x16x32_bf16 v[4:7], v[232:235], v[224:227], v[4:7]
	ds_read_b128 v[12:15], v91 offset:55360
	ds_read_b128 v[16:19], v161 offset:46144
	s_waitcnt lgkmcnt(0)
	v_mfma_f32_16x16x32_bf16 v[8:11], v[16:19], v[12:15], v[8:11]
	ds_read_b128 v[16:19], v161 offset:48448
	s_waitcnt lgkmcnt(0)
	v_mfma_f32_16x16x32_bf16 v[4:7], v[16:19], v[12:15], v[4:7]
	v_lshl_add_u64 v[12:13], s[80:81], 0, v[32:33]
	s_nop 3
	v_cvt_pk_bf16_f32 v8, v8, v9
	v_cvt_pk_bf16_f32 v9, v10, v11
	v_lshl_add_u64 v[10:11], v[12:13], 0, v[34:35]
	v_cvt_pk_bf16_f32 v4, v4, v5
	v_cvt_pk_bf16_f32 v5, v6, v7
	global_store_dwordx2 v[10:11], v[8:9], off
	global_store_dwordx2 v[10:11], v[4:5], off offset:32
	s_waitcnt lgkmcnt(0)
	s_barrier
	s_cbranch_vccnz .LBB0_945
